# combo18 + pre-pass items request the next work-queue ticket at the start of their last wave-item iteration
# baseline (speedup 1.0000x reference)
; __device__ __forceinline__ void phase_pre(bf16* UB, bf16* UC, const ScanBufs sb, int layer, const float* lb_logits, const float* gla_b, int it0, int it_end, int it_step, int lane) {
;     for (int it = it0; it < it_end; it += it_step) {
;         const int ck = it / 12, sub = it - ck * 12; const size_t row0 = (size_t)ck * 16;
;         {
;             const int type = sub < 8 ? 0 : 1, hh = type == 0 ? sub : sub - 8, ch = hh * 128 + 2 * lane, nch = type == 0 ? 1024 : 512;
;             bf16* U = type == 0 ? UB : UC; const int ld = type == 0 ? 4096 : 3584;
;             bf16* qp = U + row0 * ld + ch; bf16* fp = U + row0 * ld + (type == 0 ? 1024 : 3072) + ch; bf16* kp = U + row0 * ld + (type == 0 ? 1024 : 512) + ch;
;             float par[2];
; #pragma unroll
;             for (int e = 0; e < 2; ++e) par[e] = type == 0 ? (layer == 0 ? 0.f : 1.0f / (1.0f + __expf(lb_logits[ch + e] - lb_logits[1024 + ch + e]))) : gla_b[ch + e];
.LBB0_585:
	s_bitcmp1_b32 s7, 3
	s_cbranch_scc0 .Lqpf3_skip
	v_mov_b32_e32 v213, 1
	s_and_saveexec_b64 s[100:101], s[40:41]
	s_cbranch_execz .Lqpf3_x
	v_mov_b32_e32 v212, 1
	global_atomic_add v212, v169, v212, s[34:35] sc0
.Lqpf3_x:
	s_or_b64 exec, exec, s[100:101]
.Lqpf3_skip:
	s_mul_hi_i32 s0, s7, 0x2aaaaaab
	s_lshr_b32 s1, s0, 31
	s_ashr_i32 s0, s0, 1
	s_add_i32 s12, s0, s1
	s_mul_i32 s0, s12, -12
	s_add_i32 s0, s7, s0
	s_cmp_lt_i32 s0, 8
	s_mul_i32 s1, s12, 0xfffffa00
	s_cselect_b64 s[36:37], -1, 0
	s_add_i32 s10, s27, s1
	s_add_i32 s11, s10, 0xfffffc00
	s_cmp_gt_i32 s0, 7
	s_cselect_b64 s[0:1], -1, 0
	s_and_b64 vcc, s[0:1], exec
	s_cselect_b32 s10, s11, s10
	s_waitcnt vmcnt(10)
	v_or_b32_e32 v0, s10, v38
	v_cndmask_b32_e64 v2, 0, 1, s[30:31]
	v_ashrrev_i32_e32 v1, 31, v0
	s_mov_b64 s[10:11], -1
	v_cmp_ne_u32_e64 s[44:45], 1, v2
	s_cbranch_vccnz .LBB0_589
	s_and_b64 vcc, exec, s[44:45]
	v_mov_b32_e32 v127, 0
	s_cbranch_vccnz .LBB0_588
	v_readlane_b32 s76, v252, 35
	v_readlane_b32 s86, v252, 45
	v_readlane_b32 s87, v252, 46
	v_readlane_b32 s77, v252, 36
	v_readlane_b32 s78, v252, 37
	v_lshl_add_u64 v[2:3], v[0:1], 2, s[86:87]
	s_waitcnt vmcnt(9)
	v_add_co_u32_e32 v4, vcc, 0x1000, v2
	v_readlane_b32 s79, v252, 38
	s_nop 0
	v_addc_co_u32_e32 v5, vcc, 0, v3, vcc
	global_load_dword v2, v[2:3], off
	s_nop 0
	global_load_dword v3, v[4:5], off
	v_readlane_b32 s80, v252, 39
	v_readlane_b32 s81, v252, 40
	v_readlane_b32 s82, v252, 41
	v_readlane_b32 s83, v252, 42
	v_readlane_b32 s84, v252, 43
	v_readlane_b32 s85, v252, 44
	v_readlane_b32 s88, v252, 47
	v_readlane_b32 s89, v252, 48
	v_readlane_b32 s90, v252, 49
	v_readlane_b32 s91, v252, 50
	s_waitcnt vmcnt(0)
	v_sub_f32_e32 v2, v2, v3
	v_mul_f32_e32 v2, 0x3fb8aa3b, v2
	v_exp_f32_e32 v2, v2
	s_nop 0
	v_add_f32_e32 v2, 1.0, v2
	v_div_scale_f32 v3, s[10:11], v2, v2, 1.0
	v_rcp_f32_e32 v4, v3
	v_div_scale_f32 v5, vcc, 1.0, v2, 1.0
	v_fma_f32 v6, -v3, v4, 1.0
	v_fmac_f32_e32 v4, v6, v4
	v_mul_f32_e32 v6, v5, v4
	v_fma_f32 v7, -v3, v6, v5
	v_fmac_f32_e32 v6, v7, v4
	v_fma_f32 v3, -v3, v6, v5
	v_div_fmas_f32 v3, v3, v4, v6
	v_div_fixup_f32 v127, v3, v2, 1.0
